# v30 + group 0: 288 early input-projection units (column tiles 6..14) so that the following phase has 3 units per workgroup; reduced enumeration 4 row panels per XCD class
# speedup vs baseline: 1.0479x; 1.0108x over previous
; #define TIDV tid_opaque()
; #define BIDX bid_opaque()
; #define GDIM gdim_opaque()
; template <int KIND> DI void run_phase(PARAMS P, int l, int g) {
;     ...
;     else if constexpr (KIND == 7) {
;         { pg8::Gemm gm{(const bf16_t*)((unsigned char*)P.out + DS_MIXB), wl + WL_WOUT, gr, D, D}; pg8::StaticOrder S; S.init(gr, D, GDIM, (BIDX + GDIM / 2) % GDIM);
;           EpiRes E{X + (size_t)gbs * D}; pg8::gemm_phase<EpiRes, pg8::StaticOrder, true, true>(TIDV, lds, gm, S, E); }
;         if (g < NGROUP - 1) { const int g2 = g + 1, gr2 = grows(g2), gbs2 = gbase(g2);
;           pg8::Gemm gm{XN + (size_t)gbs2 * D, wl + WL_WIN, gr2, NIN, D}; pg8::StaticOrder S; S.init(gr2, NIN, GDIM, BIDX);
;           EpiIn E{gb, (const float*)(P.ws + WS_ROT), g2}; pg8::gemm_phase<EpiIn, pg8::StaticOrder, true, true>(TIDV, lds, gm, S, E); }
.Lk7_noff:
	s_mov_b32 s98, 0
	s_cmp_lg_u32 s92, 0x100
	s_cbranch_scc1 .Lk7_mode_done
	s_cmp_gt_u32 s34, 2
	s_cbranch_scc1 .Lk7_mode_done
	s_cmp_eq_u32 s34, 0
	s_cbranch_scc1 .Lk7_mode_g0
	s_mov_b32 s98, 1
	s_mov_b32 s99, 0x08000280
	s_cmp_eq_u32 s31, 6
	s_cbranch_scc0 .Lk7_mode_done
	s_mov_b32 s98, 2
	s_mov_b32 s99, 0x01000080
	s_branch .Lk7_mode_done
.Lk7_mode_g0:
	s_mov_b32 s98, 1
	s_mov_b32 s99, 0x09100260
	s_cmp_eq_u32 s31, 6
	s_cbranch_scc0 .Lk7_mode_done
	s_mov_b32 s98, 2
	s_mov_b32 s99, 0x0120008c

;     DI bool next(int i, Unit& u) const { if (!S.next(i / 3, u)) return false; const int z = i % 3; u.z = z; u.offA = (unsigned)z * (unsigned)(G0ROWS * 512 * 2); u.offB = (unsigned)z * (unsigned)(524288 * 2); return true; }
;     DI bool next(int i, Unit& u) const { const int j = i * G + c; if (j >= 3 * 4 * NKSL) return false; u.pm = MMAIN / 256 + j / (4 * NKSL); u.pn = (j / NKSL) & 3; const int kh = j % NKSL; u.z = kh; u.offA = (unsigned)(kh * 512); u.offB = (unsigned)(kh * 512); return true; }
;     __host__ __device__ bool next(int i, Unit& u) const {
;         const long L = (long)i * G + c; if (L >= nwg) return false;
;         int wgid = (int)L; { const int q = nwg / NXCD, r = nwg % NXCD, xcd = wgid % NXCD, off = wgid / NXCD; wgid = (xcd < r ? xcd * (q + 1) : r * (q + 1) + (xcd - r) * q) + off; }
;         const int nig = WGM * nN, gid = wgid / nig, fm = gid * WGM, gsz = (nM - fm) < WGM ? (nM - fm) : WGM;
;         u.pm = fm + ((wgid % nig) % gsz); u.pn = (wgid % nig) / gsz; return true;
.LBB0_234:
	s_cmp_eq_u32 s98, 0
	s_cbranch_scc1 .Lgi_a_done
	s_cmp_eq_u32 s98, 2
	s_cbranch_scc1 .Lgi_a_early
	s_bfe_u32 s3, s99, 0x80010
	s_sub_i32 s2, s79, s3
	s_and_b32 s2, s2, 0xff
	s_and_b32 s3, s99, 0xffff
	s_cmp_lt_u32 s2, s3
	s_cselect_b64 s[16:17], -1, 0
	s_and_b32 s3, s2, 7
	s_lshr_b32 s2, s2, 3
	s_lshl_b32 s3, s3, 2
	s_and_b32 s10, s2, 3
	s_add_i32 s4, s3, s10
	s_lshr_b32 s40, s2, 2
	s_cmp_lt_u32 s40, 6
	s_cbranch_scc1 .Lgi_a_done
	s_lshr_b32 s2, s99, 24
	s_add_i32 s40, s40, s2
	s_branch .Lgi_a_done

;     DI bool next(int i, Unit& u) const { if (!S.next(i / 3, u)) return false; const int z = i % 3; u.z = z; u.offA = (unsigned)z * (unsigned)(G0ROWS * 512 * 2); u.offB = (unsigned)z * (unsigned)(524288 * 2); return true; }
;     DI bool next(int i, Unit& u) const { const int j = i * G + c; if (j >= 3 * 4 * NKSL) return false; u.pm = MMAIN / 256 + j / (4 * NKSL); u.pn = (j / NKSL) & 3; const int kh = j % NKSL; u.z = kh; u.offA = (unsigned)(kh * 512); u.offB = (unsigned)(kh * 512); return true; }
;     __host__ __device__ bool next(int i, Unit& u) const {
;         const long L = (long)i * G + c; if (L >= nwg) return false;
;         int wgid = (int)L; { const int q = nwg / NXCD, r = nwg % NXCD, xcd = wgid % NXCD, off = wgid / NXCD; wgid = (xcd < r ? xcd * (q + 1) : r * (q + 1) + (xcd - r) * q) + off; }
;         const int nig = WGM * nN, gid = wgid / nig, fm = gid * WGM, gsz = (nM - fm) < WGM ? (nM - fm) : WGM;
;         u.pm = fm + ((wgid % nig) % gsz); u.pn = (wgid % nig) / gsz; return true;
.LBB0_240:
	s_add_i32 s36, s36, 1
	s_cmp_eq_u32 s98, 0
	s_cbranch_scc1 .Lgi_b_orig
	s_cmp_eq_u32 s98, 2
	s_cbranch_scc1 .Lgi_b_early
	s_mul_i32 s0, s36, s78
	s_bfe_u32 s1, s99, 0x80010
	s_sub_i32 s1, s79, s1
	s_and_b32 s1, s1, 0xff
	s_add_i32 s0, s0, s1
	s_and_b32 s1, s99, 0xffff
	s_cmp_lt_u32 s0, s1
	s_cselect_b64 s[38:39], -1, 0
	s_cbranch_scc0 .Lgi_b_done
	s_and_b32 s1, s0, 7
	s_lshr_b32 s0, s0, 3
	s_lshl_b32 s1, s1, 2
	s_and_b32 s3, s0, 3
	s_add_i32 s56, s1, s3
	s_lshr_b32 s54, s0, 2
	s_cmp_lt_u32 s54, 6
	s_cbranch_scc1 .Lgi_b_done
	s_lshr_b32 s0, s99, 24
	s_add_i32 s54, s54, s0
	s_branch .Lgi_b_done
